# code placement: hot loop heads (attention A g0/g1 loops, GEMM K-loops of P1/P3/P4/P5) aligned to 64 bytes
# speedup vs baseline: 1.0081x; 1.0018x over previous
; #define PG8_STAGE(bufoff, gbase, voff) do { _Pragma("unroll") for (int _i = 0; _i < 2; ++_i) \
;         __builtin_amdgcn_global_load_lds((const unsigned*)((const char*)(gbase) + (voff)[_i]), (LAS unsigned*)(lds + (bufoff) + ldsw + _i * 8192), 16, 0, 0); } while (0)
; #define PG8_LDA(dst, b, h) do { _Pragma("unroll") for (int m = 0; m < 4; ++m) _Pragma("unroll") for (int k = 0; k < 2; ++k) dst[m][k] = *(const LAS bf16x8*)(lds + PG8_SA(b, h) + aoff + m * 2048 + k * 1024); } while (0)
; #define PG8_LDB(dst, b, h) do { _Pragma("unroll") for (int n = 0; n < 2; ++n) _Pragma("unroll") for (int k = 0; k < 2; ++k) dst[n][k] = *(const LAS bf16x8*)(lds + PG8_SB(b, h) + boff + n * 2048 + k * 1024); } while (0)
; #define PG8_MMA(ai, bj, At, Bt) do { __builtin_amdgcn_s_setprio(1); _Pragma("unroll") for (int m = 0; m < 4; ++m) _Pragma("unroll") for (int n = 0; n < 2; ++n) _Pragma("unroll") for (int k = 0; k < 2; ++k) \
;         acc[ai][bj][m][n] = __builtin_amdgcn_mfma_f32_16x16x32_bf16(Bt[n][k], At[m][k], acc[ai][bj][m][n], 0, 0, 0); __builtin_amdgcn_s_setprio(0); } while (0)
; #define PG8_WAIT_V(n) asm volatile("s_waitcnt vmcnt(" #n ")" ::: "memory")
; #define PG8_WAIT_L(n) asm volatile("s_waitcnt lgkmcnt(" #n ")" ::: "memory")
; template <class Epi, bool HALO>
; __device__ __forceinline__ void gemm_phase(LAS unsigned char* lds, const bf16_t* Ag, const bf16_t* Btg, const int K, const int nM, const int nN, const int G, const int cidx, const int wave_, const Epi& E) {
;     ...
;         for (int t = 0; t < nt; t += 2) {
;             const bool last = (t == nt - 2);
;             const char* a1 = cA + (size_t)(t + 1) * kstep;
;             const char* a2 = last ? nA : cA + (size_t)(t + 2) * kstep; const char* b2 = last ? nB : cB + (size_t)(t + 2) * kstep;
;             const char* a3 = a2 + kstep; const char* b3 = b2 + kstep;
;             PG8_LDB(B0, 0, 0); PG8_LDB(B1, 0, 1); PG8_SCHED; PG8_LDA(At, 0, 0); PG8_STAGE(PG8_SA(1, 1), a1 + hstepA, voffA);
;             PG8_WAIT_V(8); PG8_WAIT_L(0); PG8_BAR; PG8_MMA(0, 0, At, B0); PG8_MMA(0, 1, At, B1); PG8_BAR; PG8_SCHED;
;     ...
; #pragma unroll
;         for (int a = 0; a < 2; ++a)
; #pragma unroll
;             for (int b = 0; b < 2; ++b)
; #pragma unroll
;                 for (int m = 0; m < 4; ++m)
; #pragma unroll
;                     for (int n = 0; n < 2; ++n) acc[a][b][m][n] = (f32x4){0.f, 0.f, 0.f, 0.f};
.LBB0_148:
	s_ashr_i32 s21, s20, 31
	s_lshl_b64 s[22:23], s[20:21], 19
	s_add_u32 s22, s28, s22
	s_addc_u32 s23, s29, s23
	s_and_b64 s[24:25], s[6:7], exec
	s_cselect_b32 s21, s23, s5
	s_cselect_b32 s41, s22, s4
	s_ashr_i32 s19, s18, 31
	s_lshl_b64 s[24:25], s[18:19], 19
	s_add_u32 s24, s0, s24
	s_addc_u32 s25, s1, s25
	s_and_b64 s[26:27], s[6:7], exec
	s_cselect_b32 s19, s25, s9
	s_cselect_b32 s42, s24, s8
	s_add_u32 s4, s4, 0x40080
	s_addc_u32 s5, s5, 0
	s_add_u32 s43, s8, 0x100
	v_mov_b32_e32 v0, 0
	s_addc_u32 s44, s9, 0
	s_mov_b32 s45, -2
	v_mov_b64_e32 v[0:1], 0
	v_mov_b64_e32 v[2:3], 0
	v_mov_b64_e32 v[4:5], 0
	v_mov_b64_e32 v[6:7], 0
	v_mov_b64_e32 v[8:9], 0
	v_mov_b64_e32 v[10:11], 0
	v_mov_b64_e32 v[12:13], 0
	v_mov_b64_e32 v[14:15], 0
	v_mov_b64_e32 v[16:17], 0
	v_mov_b64_e32 v[18:19], 0
	v_mov_b64_e32 v[20:21], 0
	v_mov_b64_e32 v[22:23], 0
	v_mov_b64_e32 v[24:25], 0
	v_mov_b64_e32 v[26:27], 0
	v_mov_b64_e32 v[28:29], 0
	v_mov_b64_e32 v[30:31], 0
	v_mov_b64_e32 v[32:33], 0
	v_mov_b64_e32 v[34:35], 0
	v_mov_b64_e32 v[36:37], 0
	v_mov_b64_e32 v[38:39], 0
	v_mov_b64_e32 v[40:41], 0
	v_mov_b64_e32 v[42:43], 0
	v_mov_b64_e32 v[44:45], 0
	v_mov_b64_e32 v[46:47], 0
	v_mov_b64_e32 v[48:49], 0
	v_mov_b64_e32 v[50:51], 0
	v_mov_b64_e32 v[52:53], 0
	v_mov_b64_e32 v[54:55], 0
	v_mov_b64_e32 v[56:57], 0
	v_mov_b64_e32 v[58:59], 0
	v_mov_b64_e32 v[60:61], 0
	v_mov_b64_e32 v[62:63], 0
	v_mov_b64_e32 v[80:81], 0
	v_mov_b64_e32 v[82:83], 0
	v_mov_b64_e32 v[84:85], 0
	v_mov_b64_e32 v[86:87], 0
	v_mov_b64_e32 v[88:89], 0
	v_mov_b64_e32 v[90:91], 0
	v_mov_b64_e32 v[92:93], 0
	v_mov_b64_e32 v[94:95], 0
	v_mov_b64_e32 v[96:97], 0
	v_mov_b64_e32 v[98:99], 0
	v_mov_b64_e32 v[100:101], 0
	v_mov_b64_e32 v[102:103], 0
	v_mov_b64_e32 v[104:105], 0
	v_mov_b64_e32 v[106:107], 0
	v_mov_b64_e32 v[108:109], 0
	v_mov_b64_e32 v[110:111], 0
	v_mov_b64_e32 v[112:113], 0
	v_mov_b64_e32 v[114:115], 0
	v_mov_b64_e32 v[116:117], 0
	v_mov_b64_e32 v[118:119], 0
	v_mov_b64_e32 v[120:121], 0
	v_mov_b64_e32 v[122:123], 0
	v_mov_b64_e32 v[124:125], 0
	v_mov_b64_e32 v[126:127], 0
	v_mov_b64_e32 v[128:129], 0
	v_mov_b64_e32 v[130:131], 0
	v_mov_b64_e32 v[132:133], 0
	v_mov_b64_e32 v[134:135], 0
	v_mov_b64_e32 v[136:137], 0
	v_mov_b64_e32 v[138:139], 0
	v_mov_b64_e32 v[140:141], 0
	v_mov_b64_e32 v[142:143], 0
	.p2align	6

; template <int MODE>
; __device__ __forceinline__ void attn_unit(const UnitArgs& A, char* lds, const int wave_) {
;     ...
;     const int tid = tid_, wid = __builtin_amdgcn_readfirstlane(tid >> 6), lane = tid & 63, r32 = lane & 31, hi = lane >> 5;
;     const int qb = wid & 3, half = wid >> 2;
;     if (wid >= 4) __builtin_amdgcn_s_setprio(1);
;     char* V_lds = lds; char* K_lds = lds + 2 * SHM_V;
;     float* ws = (float*)(lds + OFF_WS) + wid * 64; float* li_l = ws;
;     const float* lutA = (const float*)(lds + OFF_LUTA); const float* lutB = (const float*)(lds + OFF_LUTB);
;     float l_reg = 0; f32x16 o[4] = {}; bf16x8 qr[4];
;     { const bf16_t* Qw = A.Qb + (long)(qb * QBLK + r32) * NZ + half * 64 + hi * 8;
; #pragma unroll
;       for (int d0 = 0; d0 < 4; ++d0) qr[d0] = *reinterpret_cast<const bf16x8*>(Qw + d0 * 16); }
;     const int sr = tid >> 4, sc = (tid & 15) * 8, vst0 = v_st(sr, sc);
;     const int vbase = (int)(uintptr_t)V_lds + v_rd_base(lane) + (MODE == 0 ? 0 : half * 1024);
;     const int ldk = A.ldk; const unsigned ldoff = (unsigned)(sr * ldk + sc) * 2u;
;     struct { bf16x8 vs0, vs1; } sr_[1];
;     const unsigned kdoff = (unsigned)(sr * ldk + (((tid & 15) ^ (sr & 7)) * 8)) * 2u;
;     const unsigned kdst0 = (unsigned)__builtin_amdgcn_readfirstlane((int)((unsigned)(uintptr_t)K_lds + (unsigned)wid * 1024u));
;     ...
;     auto zone_of = [&](int t) -> int { const int k0 = 64 * t, qw0 = A.q0 + 32 * qb; return (k0 + 63 - qw0 <= -128) ? 0 : ((k0 - qw0 - 31 >= 128) ? 2 : 1); };
;     ...
;     auto post = [&](f32x16& p0, f32x16& p1, int t) {
;         SBAR();
;         if (MODE == 0) {
;             if (zone_of(t) == 1) { const int k0 = 64 * t, qw0 = A.q0 + 32 * qb;
;                 const float* b = lutA + A.h * LUTA_STRIDE + (k0 - qw0 - r32 + 4 * hi + 320);
; #pragma unroll
;                 for (int r = 0; r < 16; ++r) { const int c = (r & 3) + 8 * (r >> 2); p0[r] += b[c]; p1[r] += b[32 + c]; } }
;         } else if (MODE == 1) {
;             const int kr = A.tile0 + t, rq = A.q0 + (qb >> 1);
;             int rs = rq - 4; rs = rs < 0 ? 0 : rs; rs = rs > A.R - 8 ? A.R - 8 : rs;
;             if (kr < rs || kr >= rs + 8) {
; #pragma unroll
;                 for (int r = 0; r < 16; ++r) { p0[r] = NEG; p1[r] = NEG; }
;             } else {
;                 const int c = 32 * (qb & 1) + r32; int cs = c - 8; cs = cs < 0 ? 0 : cs; cs = cs > 48 ? 48 : cs;
.LBB0_314:
	s_add_i32 s84, s8, s7
	s_mul_i32 s3, s84, 0x1400
	s_mul_hi_u32 s2, s84, 0x1400
	s_add_u32 s17, s37, s3
	s_addc_u32 s18, s38, s2
	s_lshl_b32 s2, s6, 7
	s_ashr_i32 s3, s2, 31
	s_lshl_b64 s[2:3], s[2:3], 1
	s_add_u32 s24, s17, s2
	s_addc_u32 s25, s18, s3
	s_mul_i32 s31, s7, 0x1400
	s_mul_hi_u32 s30, s7, 0x1400
	s_add_u32 s6, s37, s31
	s_addc_u32 s7, s38, s30
	s_add_u32 s6, s6, s2
	s_addc_u32 s7, s7, s3
	s_and_b32 s18, s1, 3
	v_and_b32_e32 v156, 31, v40
	s_lshl_b32 s28, s18, 5
	v_or_b32_e32 v0, s28, v156
	s_ashr_i32 s17, s0, 8
	v_mul_u32_u24_e32 v144, 0x1400, v0
	v_lshl_add_u64 v[0:1], s[24:25], 0, v[144:145]
	s_lshl_b32 s24, s17, 6
	v_bfe_u32 v157, v40, 5, 1
	s_ashr_i32 s25, s24, 31
	v_lshl_add_u64 v[0:1], s[24:25], 1, v[0:1]
	v_lshlrev_b32_e32 v136, 4, v157
	v_mov_b32_e32 v137, v145
	v_lshl_add_u64 v[0:1], v[0:1], 0, v[136:137]
	global_load_dwordx4 v[108:111], v[0:1], off
	global_load_dwordx4 v[104:107], v[0:1], off offset:32
	global_load_dwordx4 v[100:103], v[0:1], off offset:64
	global_load_dwordx4 v[96:99], v[0:1], off offset:96
	s_add_u32 s24, s6, 0x400
	s_addc_u32 s25, s7, 0
	s_add_u32 s26, s6, 0x800
	s_addc_u32 s27, s7, 0
	v_and_b32_e32 v137, 63, v40
	v_lshlrev_b32_e32 v176, 8, v156
	v_and_b32_e32 v178, 15, v156
	v_lshlrev_b32_e32 v178, 4, v178
	s_lshl_b32 s99, s17, 7
	v_or_b32_e32 v179, s99, v136
	v_xor_b32_e32 v179, v179, v178
	v_add_u32_e32 v176, v176, v179
	v_add_u32_e32 v164, 0x8000, v176
	v_xor_b32_e32 v165, 32, v164
	v_xor_b32_e32 v166, 64, v164
	v_xor_b32_e32 v167, 0x60, v164
	v_and_b32_e32 v176, 3, v137
	v_lshlrev_b32_e32 v176, 3, v176
	v_bfe_u32 v178, v137, 2, 2
	v_lshlrev_b32_e32 v178, 6, v178
	v_bfe_u32 v179, v137, 4, 1
	v_lshlrev_b32_e32 v179, 5, v179
	v_bfe_u32 v180, v137, 5, 1
	v_lshlrev_b32_e32 v180, 8, v180
	v_or3_b32 v176, v176, v178, v179
	v_or_b32_e32 v168, v176, v180
	v_lshrrev_b32_e32 v176, 4, v40
	v_and_b32_e32 v178, 15, v40
	v_and_b32_e32 v179, 15, v176
	v_xor_b32_e32 v178, v178, v179
	v_lshlrev_b32_e32 v178, 4, v178
	v_mul_u32_u24_e32 v176, 0x1400, v176
	v_add_u32_e32 v169, v176, v178
	v_add_u32_e32 v170, 0x28000, v169
	v_bfe_u32 v178, v137, 2, 3
	s_bfe_u32 s99, s1, 0x10001
	s_lshl_b32 s99, s99, 3
	s_bfe_u32 s6, s1, 0x10002
	s_lshl_b32 s6, s6, 4
	s_or_b32 s99, s99, s6
	v_or_b32_e32 v178, s99, v178
	v_mul_u32_u24_e32 v178, 0x1400, v178
	s_and_b32 s99, s1, 1
	s_lshl_b32 s99, s99, 7
	v_bfe_u32 v176, v137, 5, 1
	v_lshlrev_b32_e32 v176, 6, v176
	v_and_b32_e32 v179, 3, v137
	v_lshlrev_b32_e32 v179, 4, v179
	v_add3_u32 v178, v178, v176, v179
	v_add_u32_e32 v171, s99, v178
	v_add_u32_e32 v172, 0x28000, v171
	s_lshl_b32 s33, s1, 10
	s_add_u32 s31, s33, 0x8000
	s_add_i32 s99, s8, s28
	s_sub_i32 s29, s99, 0xbf
	s_add_i32 s30, s99, 0x9f
	s_sub_i32 s35, 0x140, s99
	s_lshl_b32 s35, s35, 2
	s_add_i32 s35, s35, s19
	v_lshlrev_b32_e32 v176, 2, v157
	v_sub_u32_e32 v176, v176, v156
	v_lshlrev_b32_e32 v174, 2, v176
	v_mov_b32_e32 v176, s13
	v_sub_f32_e32 v178, s21, v176
	v_sub_f32_e32 v179, s20, v176
	s_xor_b32 s98, s13, 0x80000000
	s_sub_i32 s20, s22, 1
	v_readfirstlane_b32 s21, v178
	v_readfirstlane_b32 s22, v179
	s_mov_b32 s34, 0
	s_mov_b32 s23, 0
	s_cmp_le_i32 s23, s29
	s_cselect_b32 s9, s21, s98
	v_mov_b32_e32 v68, s9
	v_mov_b32_e32 v69, s9
	v_mov_b32_e32 v70, s9
	v_mov_b32_e32 v71, s9
	v_mov_b32_e32 v72, s9
	v_mov_b32_e32 v73, s9
	v_mov_b32_e32 v74, s9
	v_mov_b32_e32 v75, s9
	v_mov_b32_e32 v76, s9
	v_mov_b32_e32 v77, s9
	v_mov_b32_e32 v78, s9
	v_mov_b32_e32 v79, s9
	v_mov_b32_e32 v80, s9
	v_mov_b32_e32 v81, s9
	v_mov_b32_e32 v82, s9
	v_mov_b32_e32 v83, s9
	v_mov_b32_e32 v0, 0
	v_mov_b32_e32 v1, 0
	v_mov_b32_e32 v2, 0
	v_mov_b32_e32 v3, 0
	v_mov_b32_e32 v4, 0
	v_mov_b32_e32 v5, 0
	v_mov_b32_e32 v6, 0
	v_mov_b32_e32 v7, 0
	v_mov_b32_e32 v8, 0
	v_mov_b32_e32 v9, 0
	v_mov_b32_e32 v10, 0
	v_mov_b32_e32 v11, 0
	v_mov_b32_e32 v12, 0
	v_mov_b32_e32 v13, 0
	v_mov_b32_e32 v14, 0
	v_mov_b32_e32 v15, 0
	v_mov_b32_e32 v16, 0
	v_mov_b32_e32 v17, 0
	v_mov_b32_e32 v18, 0
	v_mov_b32_e32 v19, 0
	v_mov_b32_e32 v20, 0
	v_mov_b32_e32 v21, 0
	v_mov_b32_e32 v22, 0
	v_mov_b32_e32 v23, 0
	v_mov_b32_e32 v24, 0
	v_mov_b32_e32 v25, 0
	v_mov_b32_e32 v26, 0
	v_mov_b32_e32 v27, 0
	v_mov_b32_e32 v28, 0
	v_mov_b32_e32 v29, 0
	v_mov_b32_e32 v30, 0
	v_mov_b32_e32 v31, 0
	v_mov_b32_e32 v32, 0
	v_mov_b32_e32 v33, 0
	v_mov_b32_e32 v34, 0
	v_mov_b32_e32 v35, 0
	v_mov_b32_e32 v36, 0
	v_mov_b32_e32 v37, 0
	v_mov_b32_e32 v38, 0
	v_mov_b32_e32 v39, 0
	v_mov_b32_e32 v40, 0
	v_mov_b32_e32 v41, 0
	v_mov_b32_e32 v42, 0
	v_mov_b32_e32 v43, 0
	v_mov_b32_e32 v44, 0
	v_mov_b32_e32 v45, 0
	v_mov_b32_e32 v46, 0
	v_mov_b32_e32 v47, 0
	v_mov_b32_e32 v48, 0
	v_mov_b32_e32 v49, 0
	v_mov_b32_e32 v50, 0
	v_mov_b32_e32 v51, 0
	v_mov_b32_e32 v52, 0
	v_mov_b32_e32 v53, 0
	v_mov_b32_e32 v54, 0
	v_mov_b32_e32 v55, 0
	v_mov_b32_e32 v56, 0
	v_mov_b32_e32 v57, 0
	v_mov_b32_e32 v58, 0
	v_mov_b32_e32 v59, 0
	v_mov_b32_e32 v60, 0
	v_mov_b32_e32 v61, 0
	v_mov_b32_e32 v62, 0
	v_mov_b32_e32 v63, 0
	v_mov_b32_e32 v64, 0
	v_mov_b32_e32 v65, 0
	v_mov_b32_e32 v66, 0
	v_mov_b32_e32 v67, 0
	v_mov_b32_e32 v178, 0
	v_mov_b32_e32 v179, 0
	v_mov_b32_e32 v180, 0
	v_mov_b32_e32 v181, 0
	s_mov_b32 s100, 0x4000
	s_mov_b32 s101, 0x10200
	s_mov_b32 s32, 0xfffebe00
	s_mov_b32 m0, s31
	s_add_u32 s7, s31, 0x2000
	global_load_lds_dwordx4 v169, s[24:25]
	s_mov_b32 m0, s7
	s_add_u32 s31, s31, s100
	global_load_lds_dwordx4 v170, s[24:25]
	s_add_u32 s24, s24, 0x50000
	s_addc_u32 s25, s25, 0
	s_mov_b32 m0, s31
	s_add_u32 s7, s31, 0x2000
	global_load_lds_dwordx4 v169, s[24:25]
	s_mov_b32 m0, s7
	s_add_u32 s31, s31, s101
	global_load_lds_dwordx4 v170, s[24:25]
	s_add_u32 s24, s24, 0x50000
	s_addc_u32 s25, s25, 0
	s_mov_b32 m0, s31
	s_add_u32 s7, s31, 0x2000
	global_load_lds_dwordx4 v169, s[24:25]
	s_mov_b32 m0, s7
	s_add_u32 s31, s31, s32
	global_load_lds_dwordx4 v170, s[24:25]
	s_add_u32 s24, s24, 0x50000
	s_addc_u32 s25, s25, 0
	s_mov_b32 m0, s33
	s_add_u32 s7, s33, 0x2000
	global_load_lds_dwordx4 v171, s[26:27]
	s_mov_b32 m0, s7
	s_xor_b32 s33, s33, 0x4000
	global_load_lds_dwordx4 v172, s[26:27]
	s_add_u32 s26, s26, 0x50000
	s_addc_u32 s27, s27, 0
	s_waitcnt vmcnt(0)
	s_barrier
; #define SBAR() __builtin_amdgcn_sched_barrier(0)
; #define KFRAG(d0, row) (*reinterpret_cast<const bf16x8*>(Ks + KSWZ((row), (half * 64 + (d0) * 16 + hi * 8) * 2)))
; #define QK(P0, P1, KS, t) do { float v_ = -A.mshift; if (MODE == 0) { const int z_ = zone_of(t); v_ += (z_ == 0 ? A.farL : (z_ == 2 ? A.farR : 0.f)); } \
;     qkt(P0, P1, KS, qr, v_, r32, hi, half); } while (0)
; __device__ __forceinline__ void qkt(f32x16& p0, f32x16& p1, const char* Ks, const bf16x8* qr, float c0, int r32, int hi, int half) {
;     ...
;     bf16x8 a0 = KFRAG(0, r32), a1 = KFRAG(0, 32 + r32), b0 = KFRAG(1, r32), b1 = KFRAG(1, 32 + r32);
;     SBAR();
; #pragma unroll
;     for (int r = 0; r < 16; ++r) { p0[r] = c0; p1[r] = c0; }
;     SBAR();
;     p0 = __builtin_amdgcn_mfma_f32_32x32x16_bf16(a0, qr[0], p0, 0, 0, 0); p1 = __builtin_amdgcn_mfma_f32_32x32x16_bf16(a1, qr[0], p1, 0, 0, 0);
;     a0 = KFRAG(2, r32); a1 = KFRAG(2, 32 + r32);
;     SBAR();
;     p0 = __builtin_amdgcn_mfma_f32_32x32x16_bf16(b0, qr[1], p0, 0, 0, 0); p1 = __builtin_amdgcn_mfma_f32_32x32x16_bf16(b1, qr[1], p1, 0, 0, 0);
;     b0 = KFRAG(3, r32); b1 = KFRAG(3, 32 + r32);
;     SBAR();
;     p0 = __builtin_amdgcn_mfma_f32_32x32x16_bf16(a0, qr[2], p0, 0, 0, 0); p1 = __builtin_amdgcn_mfma_f32_32x32x16_bf16(a1, qr[2], p1, 0, 0, 0);
;     p0 = __builtin_amdgcn_mfma_f32_32x32x16_bf16(b0, qr[3], p0, 0, 0, 0); p1 = __builtin_amdgcn_mfma_f32_32x32x16_bf16(b1, qr[3], p1, 0, 0, 0);
; template <int MODE>
; __device__ __forceinline__ void attn_unit(const UnitArgs& A, char* lds, const int wave_) {
;     ...
;     QK(pA0, pA1, K_lds, 0); post(pA0, pA1, 0); expHalf(pA0); expHalf(pA1);
	s_cmp_lg_u32 s17, 0
	s_cbranch_scc1 .Lat_g1
	s_setprio 0
	ds_read_b128 v[224:227], v164
	ds_read_b128 v[228:231], v164 offset:8192
	ds_read_b128 v[232:235], v165
	ds_read_b128 v[236:239], v165 offset:8192
	ds_read_b128 v[240:243], v166
	ds_read_b128 v[244:247], v166 offset:8192
	ds_read_b128 v[248:251], v167
	ds_read_b128 v[188:191], v167 offset:8192
	v_add_u32_e32 v164, s100, v164
	v_add_u32_e32 v165, s100, v165
	v_add_u32_e32 v166, s100, v166
	v_add_u32_e32 v167, s100, v167
	s_waitcnt lgkmcnt(7)
	v_mfma_f32_32x32x16_bf16 v[112:127], v[224:227], v[108:111], v[68:83]
	s_waitcnt lgkmcnt(6)
	v_mfma_f32_32x32x16_bf16 v[192:207], v[228:231], v[108:111], v[68:83]
	s_waitcnt lgkmcnt(5)
	v_mfma_f32_32x32x16_bf16 v[112:127], v[232:235], v[104:107], v[112:127]
	s_waitcnt lgkmcnt(4)
	v_mfma_f32_32x32x16_bf16 v[192:207], v[236:239], v[104:107], v[192:207]
	s_waitcnt lgkmcnt(3)
	v_mfma_f32_32x32x16_bf16 v[112:127], v[240:243], v[100:103], v[112:127]
	s_waitcnt lgkmcnt(2)
	v_mfma_f32_32x32x16_bf16 v[192:207], v[244:247], v[100:103], v[192:207]
	s_waitcnt lgkmcnt(1)
	v_mfma_f32_32x32x16_bf16 v[112:127], v[248:251], v[96:99], v[112:127]
	s_waitcnt lgkmcnt(0)
	v_mfma_f32_32x32x16_bf16 v[192:207], v[188:191], v[96:99], v[192:207]
	s_nop 7
	s_nop 3
	s_barrier
	.p2align	6

; #define SBAR() __builtin_amdgcn_sched_barrier(0)
; #define KFRAG(d0, row) (*reinterpret_cast<const bf16x8*>(Ks + KSWZ((row), (half * 64 + (d0) * 16 + hi * 8) * 2)))
; #define QK(P0, P1, KS, t) do { float v_ = -A.mshift; if (MODE == 0) { const int z_ = zone_of(t); v_ += (z_ == 0 ? A.farL : (z_ == 2 ? A.farR : 0.f)); } \
;     qkt(P0, P1, KS, qr, v_, r32, hi, half); } while (0)
; __device__ __forceinline__ void qkt(f32x16& p0, f32x16& p1, const char* Ks, const bf16x8* qr, float c0, int r32, int hi, int half) {
;     ...
;     bf16x8 a0 = KFRAG(0, r32), a1 = KFRAG(0, 32 + r32), b0 = KFRAG(1, r32), b1 = KFRAG(1, 32 + r32);
;     SBAR();
; #pragma unroll
;     for (int r = 0; r < 16; ++r) { p0[r] = c0; p1[r] = c0; }
;     SBAR();
;     p0 = __builtin_amdgcn_mfma_f32_32x32x16_bf16(a0, qr[0], p0, 0, 0, 0); p1 = __builtin_amdgcn_mfma_f32_32x32x16_bf16(a1, qr[0], p1, 0, 0, 0);
;     a0 = KFRAG(2, r32); a1 = KFRAG(2, 32 + r32);
;     SBAR();
;     p0 = __builtin_amdgcn_mfma_f32_32x32x16_bf16(b0, qr[1], p0, 0, 0, 0); p1 = __builtin_amdgcn_mfma_f32_32x32x16_bf16(b1, qr[1], p1, 0, 0, 0);
;     b0 = KFRAG(3, r32); b1 = KFRAG(3, 32 + r32);
;     SBAR();
;     p0 = __builtin_amdgcn_mfma_f32_32x32x16_bf16(a0, qr[2], p0, 0, 0, 0); p1 = __builtin_amdgcn_mfma_f32_32x32x16_bf16(a1, qr[2], p1, 0, 0, 0);
;     p0 = __builtin_amdgcn_mfma_f32_32x32x16_bf16(b0, qr[3], p0, 0, 0, 0); p1 = __builtin_amdgcn_mfma_f32_32x32x16_bf16(b1, qr[3], p1, 0, 0, 0);
; template <int MODE>
; __device__ __forceinline__ void attn_unit(const UnitArgs& A, char* lds, const int wave_) {
;     ...
;     QK(pA0, pA1, K_lds, 0); post(pA0, pA1, 0); expHalf(pA0); expHalf(pA1);
.Lat_g1:
	s_barrier
	s_setprio 0
	ds_read_b128 v[224:227], v164
	ds_read_b128 v[228:231], v164 offset:8192
	ds_read_b128 v[232:235], v165
	ds_read_b128 v[236:239], v165 offset:8192
	ds_read_b128 v[240:243], v166
	ds_read_b128 v[244:247], v166 offset:8192
	ds_read_b128 v[248:251], v167
	ds_read_b128 v[188:191], v167 offset:8192
	v_add_u32_e32 v164, s100, v164
	v_add_u32_e32 v165, s100, v165
	v_add_u32_e32 v166, s100, v166
	v_add_u32_e32 v167, s100, v167
	s_waitcnt lgkmcnt(7)
	v_mfma_f32_32x32x16_bf16 v[112:127], v[224:227], v[108:111], v[68:83]
	s_waitcnt lgkmcnt(6)
	v_mfma_f32_32x32x16_bf16 v[192:207], v[228:231], v[108:111], v[68:83]
	s_waitcnt lgkmcnt(5)
	v_mfma_f32_32x32x16_bf16 v[112:127], v[232:235], v[104:107], v[112:127]
	s_waitcnt lgkmcnt(4)
	v_mfma_f32_32x32x16_bf16 v[192:207], v[236:239], v[104:107], v[192:207]
	s_waitcnt lgkmcnt(3)
	v_mfma_f32_32x32x16_bf16 v[112:127], v[240:243], v[100:103], v[112:127]
	s_waitcnt lgkmcnt(2)
	v_mfma_f32_32x32x16_bf16 v[192:207], v[244:247], v[100:103], v[192:207]
	s_waitcnt lgkmcnt(1)
	v_mfma_f32_32x32x16_bf16 v[112:127], v[248:251], v[96:99], v[112:127]
	s_waitcnt lgkmcnt(0)
	v_mfma_f32_32x32x16_bf16 v[192:207], v[188:191], v[96:99], v[192:207]
	s_nop 7
	s_nop 3
	s_barrier
	.p2align	6

; #define PG8_STAGE(bufoff, gbase, voff) do { _Pragma("unroll") for (int _i = 0; _i < 2; ++_i) \
;         __builtin_amdgcn_global_load_lds((const unsigned*)((const char*)(gbase) + (voff)[_i]), (LAS unsigned*)(lds + (bufoff) + ldsw + _i * 8192), 16, 0, 0); } while (0)
; #define PG8_LDA(dst, b, h) do { _Pragma("unroll") for (int m = 0; m < 4; ++m) _Pragma("unroll") for (int k = 0; k < 2; ++k) dst[m][k] = *(const LAS bf16x8*)(lds + PG8_SA(b, h) + aoff + m * 2048 + k * 1024); } while (0)
; #define PG8_LDB(dst, b, h) do { _Pragma("unroll") for (int n = 0; n < 2; ++n) _Pragma("unroll") for (int k = 0; k < 2; ++k) dst[n][k] = *(const LAS bf16x8*)(lds + PG8_SB(b, h) + boff + n * 2048 + k * 1024); } while (0)
; #define PG8_MMA(ai, bj, At, Bt) do { __builtin_amdgcn_s_setprio(1); _Pragma("unroll") for (int m = 0; m < 4; ++m) _Pragma("unroll") for (int n = 0; n < 2; ++n) _Pragma("unroll") for (int k = 0; k < 2; ++k) \
;         acc[ai][bj][m][n] = __builtin_amdgcn_mfma_f32_16x16x32_bf16(Bt[n][k], At[m][k], acc[ai][bj][m][n], 0, 0, 0); __builtin_amdgcn_s_setprio(0); } while (0)
; #define PG8_WAIT_V(n) asm volatile("s_waitcnt vmcnt(" #n ")" ::: "memory")
; #define PG8_WAIT_L(n) asm volatile("s_waitcnt lgkmcnt(" #n ")" ::: "memory")
; template <class Epi, bool HALO>
; __device__ __forceinline__ void gemm_phase(LAS unsigned char* lds, const bf16_t* Ag, const bf16_t* Btg, const int K, const int nM, const int nN, const int G, const int cidx, const int wave_, const Epi& E) {
;     ...
;         for (int t = 0; t < nt; t += 2) {
;             const bool last = (t == nt - 2);
;             const char* a1 = cA + (size_t)(t + 1) * kstep;
;             const char* a2 = last ? nA : cA + (size_t)(t + 2) * kstep; const char* b2 = last ? nB : cB + (size_t)(t + 2) * kstep;
;             const char* a3 = a2 + kstep; const char* b3 = b2 + kstep;
;             PG8_LDB(B0, 0, 0); PG8_LDB(B1, 0, 1); PG8_SCHED; PG8_LDA(At, 0, 0); PG8_STAGE(PG8_SA(1, 1), a1 + hstepA, voffA);
;             PG8_WAIT_V(8); PG8_WAIT_L(0); PG8_BAR; PG8_MMA(0, 0, At, B0); PG8_MMA(0, 1, At, B1); PG8_BAR; PG8_SCHED;
;     ...
; #pragma unroll
;         for (int a = 0; a < 2; ++a)
; #pragma unroll
;             for (int b = 0; b < 2; ++b)
; #pragma unroll
;                 for (int m = 0; m < 4; ++m)
; #pragma unroll
;                     for (int n = 0; n < 2; ++n) acc[a][b][m][n] = (f32x4){0.f, 0.f, 0.f, 0.f};
.LBB0_696:
	s_ashr_i32 s19, s18, 31
	s_lshl_b64 s[20:21], s[18:19], 19
	s_add_u32 s20, s0, s20
	s_addc_u32 s21, s1, s21
	s_and_b64 s[22:23], s[6:7], exec
	s_cselect_b32 s19, s21, s25
	s_cselect_b32 s44, s20, s24
	s_ashr_i32 s15, s14, 31
	s_lshl_b64 s[22:23], s[14:15], 19
	s_add_u32 s22, s30, s22
	s_addc_u32 s23, s31, s23
	s_and_b64 s[28:29], s[6:7], exec
	s_cselect_b32 s15, s23, s27
	s_cselect_b32 s45, s22, s26
	s_add_u32 s24, s24, 0x40080
	s_addc_u32 s25, s25, 0
	s_add_u32 s46, s26, 0x100
	v_mov_b32_e32 v0, 0
	s_addc_u32 s47, s27, 0
	s_mov_b32 s48, -2
	v_mov_b64_e32 v[0:1], 0
	v_mov_b64_e32 v[2:3], 0
	v_mov_b64_e32 v[4:5], 0
	v_mov_b64_e32 v[6:7], 0
	v_mov_b64_e32 v[8:9], 0
	v_mov_b64_e32 v[10:11], 0
	v_mov_b64_e32 v[12:13], 0
	v_mov_b64_e32 v[14:15], 0
	v_mov_b64_e32 v[16:17], 0
	v_mov_b64_e32 v[18:19], 0
	v_mov_b64_e32 v[20:21], 0
	v_mov_b64_e32 v[22:23], 0
	v_mov_b64_e32 v[24:25], 0
	v_mov_b64_e32 v[26:27], 0
	v_mov_b64_e32 v[28:29], 0
	v_mov_b64_e32 v[30:31], 0
	v_mov_b64_e32 v[32:33], 0
	v_mov_b64_e32 v[34:35], 0
	v_mov_b64_e32 v[36:37], 0
	v_mov_b64_e32 v[38:39], 0
	v_mov_b64_e32 v[40:41], 0
	v_mov_b64_e32 v[42:43], 0
	v_mov_b64_e32 v[44:45], 0
	v_mov_b64_e32 v[46:47], 0
	v_mov_b64_e32 v[48:49], 0
	v_mov_b64_e32 v[50:51], 0
	v_mov_b64_e32 v[52:53], 0
	v_mov_b64_e32 v[54:55], 0
	v_mov_b64_e32 v[56:57], 0
	v_mov_b64_e32 v[58:59], 0
	v_mov_b64_e32 v[60:61], 0
	v_mov_b64_e32 v[62:63], 0
	v_mov_b64_e32 v[64:65], 0
	v_mov_b64_e32 v[66:67], 0
	v_mov_b64_e32 v[68:69], 0
	v_mov_b64_e32 v[70:71], 0
	v_mov_b64_e32 v[72:73], 0
	v_mov_b64_e32 v[74:75], 0
	v_mov_b64_e32 v[76:77], 0
	v_mov_b64_e32 v[78:79], 0
	v_mov_b64_e32 v[80:81], 0
	v_mov_b64_e32 v[82:83], 0
	v_mov_b64_e32 v[84:85], 0
	v_mov_b64_e32 v[86:87], 0
	v_mov_b64_e32 v[88:89], 0
	v_mov_b64_e32 v[90:91], 0
	v_mov_b64_e32 v[92:93], 0
	v_mov_b64_e32 v[94:95], 0
	v_mov_b64_e32 v[96:97], 0
	v_mov_b64_e32 v[98:99], 0
	v_mov_b64_e32 v[100:101], 0
	v_mov_b64_e32 v[102:103], 0
	v_mov_b64_e32 v[104:105], 0
	v_mov_b64_e32 v[106:107], 0
	v_mov_b64_e32 v[108:109], 0
	v_mov_b64_e32 v[110:111], 0
	v_mov_b64_e32 v[112:113], 0
	v_mov_b64_e32 v[114:115], 0
	v_mov_b64_e32 v[116:117], 0
	v_mov_b64_e32 v[118:119], 0
	v_mov_b64_e32 v[120:121], 0
	v_mov_b64_e32 v[122:123], 0
	v_mov_b64_e32 v[124:125], 0
	v_mov_b64_e32 v[126:127], 0
	.p2align	6

; template <class Epi, bool HALO>
; __device__ __forceinline__ void gemm_phase(LAS unsigned char* lds, const bf16_t* Ag, const bf16_t* Btg, const int K, const int nM, const int nN, const int G, const int cidx, const int wave_, const Epi& E) {
;     ...
; #pragma unroll
;         for (int a = 0; a < 2; ++a)
; #pragma unroll
;             for (int b = 0; b < 2; ++b)
; #pragma unroll
;                 for (int m = 0; m < 4; ++m)
; #pragma unroll
;                     for (int n = 0; n < 2; ++n) acc[a][b][m][n] = (f32x4){0.f, 0.f, 0.f, 0.f};
;     __device__ __forceinline__ void operator()(const f32x4 (&acc)[2][2][4][2], const Unit& u, int wr, int wc, int fr, int fq) const {
;         int seqbase, t0, slen; halo_decode(u.pm, seqbase, t0, slen);
;         const f32x4* ct = (const f32x4*)(CT + (size_t)(128 * u.pn) * 8) + (32 * wc + 8 * fq) * 2;
;         const bool f0 = (fr == 0), f15 = (fr == 15);
; #pragma unroll
;         for (int ai = 0; ai < 2; ++ai) {
;             const int tbase = t0 + 62 * (2 * ai + wr) - 1;
;             float rs[4];
; #pragma unroll
;             for (int m = 0; m < 4; ++m) { const int t = tbase + 16 * m + fr; const bool vin = (t >= 0) && (t < slen); const int grow = seqbase + (vin ? t : 0);
;                 const f32x4 p = *(const f32x4*)(PS + (size_t)grow * 16 + 4 * fq); float s = (p[0] + p[1]) + (p[2] + p[3]); s = bfly_add<16>(s); s = bfly_add<32>(s); rs[m] = vin ? rsqrtf(s * (1.f / DM) + EPS) : 0.f; }
EC2_join:
	s_mul_i32 s86, s86, 0xf8
	s_bfe_u32 s89, s81, 0x10008
	s_mul_i32 s89, s89, 62
	s_add_i32 s89, s89, s86
	s_add_i32 s89, s89, -1
	v_mbcnt_lo_u32_b32 v176, -1, 0
	v_mbcnt_hi_u32_b32 v176, -1, v176
	v_and_b32_e32 v164, 15, v176
	v_lshlrev_b32_e32 v164, 2, v164
	v_bfe_u32 v165, v176, 4, 2
	v_lshlrev_b32_e32 v172, 8, v165
	v_lshlrev_b32_e32 v165, 4, v165
	v_add_u32_e32 v174, s89, v164
	v_lshrrev_b32_e32 v176, 4, v165
	v_add_u32_e32 v176, v176, v174
	v_cmp_gt_u32_e32 vcc, s91, v176
	s_nop 1
	v_cndmask_b32_e32 v176, 0, v176, vcc
	v_add_u32_e32 v176, s88, v176
	v_lshlrev_b32_e32 v252, 6, v176
	global_load_dwordx4 v[240:243], v252, s[70:71]
	global_load_dwordx4 v[244:247], v252, s[70:71] offset:16
	global_load_dwordx4 v[248:251], v252, s[70:71] offset:32
	global_load_dwordx4 v[160:163], v252, s[70:71] offset:48
	s_ashr_i32 s29, s28, 31
	s_lshl_b64 s[20:21], s[28:29], 19
	s_add_u32 s34, s38, s20
	s_addc_u32 s35, s39, s21
	s_and_b64 s[14:15], s[14:15], exec
	s_cselect_b32 s20, s35, s19
	s_cselect_b32 s21, s34, s18
	s_add_u32 s2, s2, 0x3e080
	s_addc_u32 s3, s3, 0
	s_add_u32 s29, s18, 0x100
	v_mov_b32_e32 v0, 0
	s_addc_u32 s37, s19, 0
	s_mov_b32 s51, -2
	v_mov_b64_e32 v[0:1], 0
	v_mov_b64_e32 v[2:3], 0
	v_mov_b64_e32 v[4:5], 0
	v_mov_b64_e32 v[6:7], 0
	v_mov_b64_e32 v[8:9], 0
	v_mov_b64_e32 v[10:11], 0
	v_mov_b64_e32 v[12:13], 0
	v_mov_b64_e32 v[14:15], 0
	v_mov_b64_e32 v[16:17], 0
	v_mov_b64_e32 v[18:19], 0
	v_mov_b64_e32 v[20:21], 0
	v_mov_b64_e32 v[22:23], 0
	v_mov_b64_e32 v[24:25], 0
	v_mov_b64_e32 v[26:27], 0
	v_mov_b64_e32 v[28:29], 0
	v_mov_b64_e32 v[30:31], 0
	v_mov_b64_e32 v[32:33], 0
	v_mov_b64_e32 v[34:35], 0
	v_mov_b64_e32 v[36:37], 0
	v_mov_b64_e32 v[38:39], 0
	v_mov_b64_e32 v[40:41], 0
	v_mov_b64_e32 v[42:43], 0
	v_mov_b64_e32 v[44:45], 0
	v_mov_b64_e32 v[46:47], 0
	v_mov_b64_e32 v[48:49], 0
	v_mov_b64_e32 v[50:51], 0
	v_mov_b64_e32 v[52:53], 0
	v_mov_b64_e32 v[54:55], 0
	v_mov_b64_e32 v[56:57], 0
	v_mov_b64_e32 v[58:59], 0
	v_mov_b64_e32 v[60:61], 0
	v_mov_b64_e32 v[62:63], 0
	v_mov_b64_e32 v[64:65], 0
	v_mov_b64_e32 v[66:67], 0
	v_mov_b64_e32 v[68:69], 0
	v_mov_b64_e32 v[70:71], 0
	v_mov_b64_e32 v[72:73], 0
	v_mov_b64_e32 v[74:75], 0
	v_mov_b64_e32 v[76:77], 0
	v_mov_b64_e32 v[78:79], 0
	v_mov_b64_e32 v[80:81], 0
	v_mov_b64_e32 v[82:83], 0
	v_mov_b64_e32 v[84:85], 0
	v_mov_b64_e32 v[86:87], 0
	v_mov_b64_e32 v[88:89], 0
	v_mov_b64_e32 v[90:91], 0
	v_mov_b64_e32 v[92:93], 0
	v_mov_b64_e32 v[94:95], 0
	v_mov_b64_e32 v[96:97], 0
	v_mov_b64_e32 v[98:99], 0
	v_mov_b64_e32 v[100:101], 0
	v_mov_b64_e32 v[102:103], 0
	v_mov_b64_e32 v[104:105], 0
	v_mov_b64_e32 v[106:107], 0
	v_mov_b64_e32 v[108:109], 0
	v_mov_b64_e32 v[110:111], 0
	v_mov_b64_e32 v[112:113], 0
	v_mov_b64_e32 v[114:115], 0
	v_mov_b64_e32 v[116:117], 0
	v_mov_b64_e32 v[118:119], 0
	v_mov_b64_e32 v[120:121], 0
	v_mov_b64_e32 v[122:123], 0
	v_mov_b64_e32 v[124:125], 0
	v_mov_b64_e32 v[126:127], 0
	.p2align	6

; #define PG8_STAGE(bufoff, gbase, voff) do { _Pragma("unroll") for (int _i = 0; _i < 2; ++_i) \
;         __builtin_amdgcn_global_load_lds((const unsigned*)((const char*)(gbase) + (voff)[_i]), (LAS unsigned*)(lds + (bufoff) + ldsw + _i * 8192), 16, 0, 0); } while (0)
; #define PG8_LDA(dst, b, h) do { _Pragma("unroll") for (int m = 0; m < 4; ++m) _Pragma("unroll") for (int k = 0; k < 2; ++k) dst[m][k] = *(const LAS bf16x8*)(lds + PG8_SA(b, h) + aoff + m * 2048 + k * 1024); } while (0)
; #define PG8_LDB(dst, b, h) do { _Pragma("unroll") for (int n = 0; n < 2; ++n) _Pragma("unroll") for (int k = 0; k < 2; ++k) dst[n][k] = *(const LAS bf16x8*)(lds + PG8_SB(b, h) + boff + n * 2048 + k * 1024); } while (0)
; #define PG8_MMA(ai, bj, At, Bt) do { __builtin_amdgcn_s_setprio(1); _Pragma("unroll") for (int m = 0; m < 4; ++m) _Pragma("unroll") for (int n = 0; n < 2; ++n) _Pragma("unroll") for (int k = 0; k < 2; ++k) \
;         acc[ai][bj][m][n] = __builtin_amdgcn_mfma_f32_16x16x32_bf16(Bt[n][k], At[m][k], acc[ai][bj][m][n], 0, 0, 0); __builtin_amdgcn_s_setprio(0); } while (0)
; #define PG8_WAIT_V(n) asm volatile("s_waitcnt vmcnt(" #n ")" ::: "memory")
; #define PG8_WAIT_L(n) asm volatile("s_waitcnt lgkmcnt(" #n ")" ::: "memory")
; template <class Epi, bool HALO>
; __device__ __forceinline__ void gemm_phase(LAS unsigned char* lds, const bf16_t* Ag, const bf16_t* Btg, const int K, const int nM, const int nN, const int G, const int cidx, const int wave_, const Epi& E) {
;     ...
;         for (int t = 0; t < nt; t += 2) {
;             const bool last = (t == nt - 2);
;             const char* a1 = cA + (size_t)(t + 1) * kstep;
;             const char* a2 = last ? nA : cA + (size_t)(t + 2) * kstep; const char* b2 = last ? nB : cB + (size_t)(t + 2) * kstep;
;             const char* a3 = a2 + kstep; const char* b3 = b2 + kstep;
;             PG8_LDB(B0, 0, 0); PG8_LDB(B1, 0, 1); PG8_SCHED; PG8_LDA(At, 0, 0); PG8_STAGE(PG8_SA(1, 1), a1 + hstepA, voffA);
;             PG8_WAIT_V(8); PG8_WAIT_L(0); PG8_BAR; PG8_MMA(0, 0, At, B0); PG8_MMA(0, 1, At, B1); PG8_BAR; PG8_SCHED;
;     ...
; #pragma unroll
;         for (int a = 0; a < 2; ++a)
; #pragma unroll
;             for (int b = 0; b < 2; ++b)
; #pragma unroll
;                 for (int m = 0; m < 4; ++m)
; #pragma unroll
;                     for (int n = 0; n < 2; ++n) acc[a][b][m][n] = (f32x4){0.f, 0.f, 0.f, 0.f};
.LBB0_878:
	s_add_u32 s46, s26, 0x100
	v_mov_b32_e32 v0, 0
	s_addc_u32 s47, s27, 0
	s_mov_b32 s48, -2
	v_mov_b64_e32 v[0:1], 0
	v_mov_b64_e32 v[2:3], 0
	v_mov_b64_e32 v[4:5], 0
	v_mov_b64_e32 v[6:7], 0
	v_mov_b64_e32 v[8:9], 0
	v_mov_b64_e32 v[10:11], 0
	v_mov_b64_e32 v[12:13], 0
	v_mov_b64_e32 v[14:15], 0
	v_mov_b64_e32 v[16:17], 0
	v_mov_b64_e32 v[18:19], 0
	v_mov_b64_e32 v[20:21], 0
	v_mov_b64_e32 v[22:23], 0
	v_mov_b64_e32 v[24:25], 0
	v_mov_b64_e32 v[26:27], 0
	v_mov_b64_e32 v[28:29], 0
	v_mov_b64_e32 v[30:31], 0
	v_mov_b64_e32 v[32:33], 0
	v_mov_b64_e32 v[34:35], 0
	v_mov_b64_e32 v[36:37], 0
	v_mov_b64_e32 v[38:39], 0
	v_mov_b64_e32 v[40:41], 0
	v_mov_b64_e32 v[42:43], 0
	v_mov_b64_e32 v[44:45], 0
	v_mov_b64_e32 v[46:47], 0
	v_mov_b64_e32 v[48:49], 0
	v_mov_b64_e32 v[50:51], 0
	v_mov_b64_e32 v[52:53], 0
	v_mov_b64_e32 v[54:55], 0
	v_mov_b64_e32 v[56:57], 0
	v_mov_b64_e32 v[58:59], 0
	v_mov_b64_e32 v[60:61], 0
	v_mov_b64_e32 v[62:63], 0
	v_mov_b64_e32 v[64:65], 0
	v_mov_b64_e32 v[66:67], 0
	v_mov_b64_e32 v[68:69], 0
	v_mov_b64_e32 v[70:71], 0
	v_mov_b64_e32 v[72:73], 0
	v_mov_b64_e32 v[74:75], 0
	v_mov_b64_e32 v[76:77], 0
	v_mov_b64_e32 v[78:79], 0
	v_mov_b64_e32 v[80:81], 0
	v_mov_b64_e32 v[82:83], 0
	v_mov_b64_e32 v[84:85], 0
	v_mov_b64_e32 v[86:87], 0
	v_mov_b64_e32 v[88:89], 0
	v_mov_b64_e32 v[90:91], 0
	v_mov_b64_e32 v[92:93], 0
	v_mov_b64_e32 v[94:95], 0
	v_mov_b64_e32 v[96:97], 0
	v_mov_b64_e32 v[98:99], 0
	v_mov_b64_e32 v[100:101], 0
	v_mov_b64_e32 v[102:103], 0
	v_mov_b64_e32 v[104:105], 0
	v_mov_b64_e32 v[106:107], 0
	v_mov_b64_e32 v[108:109], 0
	v_mov_b64_e32 v[110:111], 0
	v_mov_b64_e32 v[112:113], 0
	v_mov_b64_e32 v[114:115], 0
	v_mov_b64_e32 v[116:117], 0
	v_mov_b64_e32 v[118:119], 0
	v_mov_b64_e32 v[120:121], 0
	v_mov_b64_e32 v[122:123], 0
	v_mov_b64_e32 v[124:125], 0
	v_mov_b64_e32 v[126:127], 0
	.p2align	6
